# plus S5 carry on thin workgroups 0..31 instead of behind the gate tiles
# speedup vs baseline: 1.0042x; 1.0004x over previous
; __global__ void __launch_bounds__(512, 2) mega_fwd(Args args) {
;     ...
;     for (int l = 0; l < DEPTH; ++l) {
;         const int Mrows = (l == DEPTH - 1) ? NLAT : NTOK;
;         const int cb_ = (Ggemm - GRID_C >= 32) ? GRID_C : 0;
;         const int eC = ECR * (Ggemm - GRID_C), eC2 = eC, eD = eC2 + 1 * (Ggemm - GRID_D);
;     ...
;             { PH_BEGIN if (cb_ == 0 && bid < 32) { CARRY_BLOCK(bid) } },
;     ...
;             { PH_BEGIN for (int r_ = 0; r_ < REP_GMLP; ++r_) for (int u = G - 1 - bid; u < NTOK / 128; u += G) gmlp_unit(a, l, u, ldsL, tid); }
;             { PH_BEGIN for (int r_ = 0; r_ < REP_CONV; ++r_) for (int u = bid; u < NTOK / 32; u += G) conv_unit(a, l, u, ldsL, tid); }
;             { PH_BEGIN for (int r_ = 0; r_ < REP_ATTN; ++r_) for (int u = bid; u < 1024 + 32; u += G) attn_unit(a, l, u, ldsL, tid); }
;             { PH_BEGIN for (int r_ = 0; r_ < REP_S5S; ++r_) for (int u = G - 1 - bid; u < 352; u += G) s5_state_unit(a, u, ldsL, tid); }
;             { PH_BEGIN shw_rows(a, l, 3, WSP(const bf16, WS_WF1), DFF, WSP(float, WS_SHW), nullptr, ldsL, tid, gw, NGW); },
;     ...
;             GATES_EARLY(0, eC) { PH_BEGIN if (cb_ != 0 && bid - cb_ < 32) { CARRY_BLOCK(bid - cb_) } } )
.LBB0_160:
	s_or_b64 exec, exec, s[0:1]
	s_min_i32 s92, s87, 0xb0
	s_sub_i32 s0, s87, s92
	s_cmp_gt_i32 s0, 31
	s_mov_b32 s1, 0
	s_mul_i32 s75, s0, 8
	s_cmp_lt_i32 s81, s92
	s_cselect_b64 s[2:3], -1, 0
	s_cmp_ge_i32 s81, s92
	v_writelane_b32 v254, s2, 0
	s_cselect_b64 s[94:95], -1, 0
	s_cmp_eq_u32 s1, 0
	v_writelane_b32 v254, s3, 1
	s_cselect_b64 s[2:3], -1, 0
	v_writelane_b32 v254, s2, 2
	s_cmp_lg_u32 s1, 0
	s_mul_i32 s90, s0, 7
	v_writelane_b32 v254, s3, 3
	v_writelane_b32 v254, s1, 4
	s_cselect_b64 s[0:1], -1, 0
	v_writelane_b32 v254, s0, 5
	s_add_i32 s61, 0, 0x10400
	s_add_i32 s76, 0, 0x14400
	v_writelane_b32 v254, s1, 6
	s_add_i32 s0, 0, 0x18400
	v_writelane_b32 v254, s0, 7
	s_add_i32 s0, 0, 0x20020
	v_writelane_b32 v254, s0, 8
	s_add_i32 s0, 0, 0x20024
	v_writelane_b32 v254, s0, 9
	s_add_i32 s0, 0, 0x10200
	v_writelane_b32 v254, s0, 10
	s_mov_b64 s[0:1], 0
	v_writelane_b32 v254, s0, 11
	s_mov_b32 s80, 0x8000
	v_mov_b32_e32 v250, 0x358637bd
	v_writelane_b32 v254, s1, 12
	s_mov_b64 s[0:1], 0x40000
	v_writelane_b32 v254, s0, 13
	s_mov_b32 s97, 0xf800000
	v_mov_b32_e32 v251, 0x260
	v_writelane_b32 v254, s1, 14
	s_mov_b64 s[0:1], 0
	v_writelane_b32 v254, s0, 15
	s_movk_i32 s64, 0x7fff
	s_movk_i32 s86, 0x3ff
	v_writelane_b32 v254, s1, 16
	v_writelane_b32 v254, s61, 17
	v_writelane_b32 v254, s76, 18
	v_writelane_b32 v254, s79, 19
	v_writelane_b32 v254, s87, 20
	v_writelane_b32 v254, s81, 21
	v_writelane_b32 v254, s82, 22
	s_movk_i32 s66, 0x1000
	s_mov_b32 s67, 0x56801000
	v_writelane_b32 v254, s83, 23
	v_writelane_b32 v254, s84, 24
	s_mov_b32 s68, 0x57001000
	s_mov_b32 s69, 0x57801000
	v_writelane_b32 v254, s85, 25
	v_writelane_b32 v254, s93, 26
	v_writelane_b32 v254, s88, 27
	s_mov_b32 s70, 0x58001000
	s_movk_i32 s60, 0x4000
	v_writelane_b32 v254, s89, 28
	v_writelane_b32 v254, s92, 29
	v_writelane_b32 v254, s90, 30
	v_writelane_b32 v254, s75, 31
	v_writelane_b32 v254, s94, 32
	s_add_i32 s33, 0, 0x14000
	s_movk_i32 s65, 0x67f
	v_mov_b32_e32 v252, 1.0
	s_movk_i32 s30, 0x41
	s_movk_i32 s77, 0x7dff
	s_mov_b32 s78, 0x200000
	s_mov_b32 s74, 0x240000
	s_mov_b32 s71, 0x280000
	s_mov_b32 s72, 0x2c0000
	v_mov_b32_e32 v253, 0xf149f2ca
	v_mov_b32_e32 v209, 0
	s_mov_b32 s96, 0
	s_mov_b32 s59, 0
	s_mov_b64 s[2:3], 0x80
	s_mov_b64 s[42:43], 0x14a00400
	v_writelane_b32 v254, s95, 33
	s_waitcnt lgkmcnt(0)
	s_barrier
	s_branch .LBB0_163
